# rowpass<1>: the 12 second-stage parameter-row loads (pre-norm weight, scale, shift for both halves) issued with the token's first load batch into free VGPRs instead of after the first rms-norm; on top
# baseline (speedup 1.0000x reference)
.LBB0_1073:
	v_mov_b32_e32 v0, v217
	v_mov_b32_e32 v27, v217
	v_ashrrev_i32_e32 v0, 4, v0
	v_and_b32_e32 v0, -4, v0
	v_add3_u32 v12, v15, s34, v0
	v_add3_u32 v0, v0, v15, s43
	v_lshrrev_b32_e32 v0, 12, v0
	v_ashrrev_i32_e32 v13, 31, v12
	v_lshlrev_b32_e32 v94, 3, v27
	v_add_u32_e32 v4, 1, v0
	v_lshlrev_b64 v[0:1], 12, v[12:13]
	v_and_b32_e32 v14, 0x1f8, v94
	v_lshl_add_u64 v[0:1], s[18:19], 0, v[0:1]
	v_lshlrev_b64 v[2:3], 11, v[12:13]
	v_lshlrev_b32_e32 v16, 2, v14
	v_lshl_add_u64 v[2:3], s[6:7], 0, v[2:3]
	v_lshl_add_u64 v[10:11], v[0:1], 0, v[16:17]
	v_cmp_lt_i32_e64 s[0:1], s2, v12
	v_lshlrev_b32_e32 v0, 1, v14
	v_mov_b32_e32 v1, v17
	v_cndmask_b32_e64 v8, 0, v4, s[0:1]
	v_lshl_add_u64 v[4:5], v[2:3], 0, v[0:1]
	global_load_dwordx4 v[0:3], v[4:5], off
	s_nop 0
	global_load_dwordx4 v[4:7], v[4:5], off offset:1024
	v_cmp_lt_i32_e64 s[0:1], v221, v220
	v_add_u32_e32 v18, s25, v8
	v_or_b32_e32 v26, 0x200, v14
	v_cndmask_b32_e64 v9, v218, v221, s[0:1]
	v_cmp_lt_i32_e64 s[0:1], v222, v220
	v_lshlrev_b32_e32 v95, 2, v9
	v_mov_b32_e32 v19, v17
	v_cndmask_b32_e64 v9, v218, v222, s[0:1]
	v_cmp_lt_i32_e64 s[0:1], v223, v220
	v_lshlrev_b32_e32 v96, 2, v9
	s_add_i32 s34, s34, 1
	v_cndmask_b32_e64 v9, v218, v223, s[0:1]
	v_cmp_lt_i32_e64 s[0:1], v224, v220
	v_lshlrev_b32_e32 v97, 2, v9
	s_cmp_lg_u32 s34, 4
	v_cndmask_b32_e64 v9, v218, v224, s[0:1]
	v_cmp_lt_i32_e64 s[0:1], v225, v220
	v_lshlrev_b32_e32 v98, 2, v9
	s_waitcnt vmcnt(1)
	v_and_b32_e32 v69, 0xffff0000, v0
	v_cndmask_b32_e64 v9, v218, v225, s[0:1]
	v_cmp_lt_i32_e64 s[0:1], v226, v220
	v_lshlrev_b32_e32 v99, 2, v9
	v_lshlrev_b32_e32 v68, 16, v0
	v_cndmask_b32_e64 v9, v218, v226, s[0:1]
	v_lshlrev_b32_e32 v100, 2, v9
	v_mov_b64_e32 v[8:9], s[28:29]
	v_mad_u64_u32 v[8:9], s[0:1], v18, s24, v[8:9]
	v_lshl_add_u64 v[20:21], v[8:9], 0, s[50:51]
	v_lshl_add_u64 v[24:25], v[20:21], 0, v[16:17]
	v_lshlrev_b32_e32 v18, 2, v26
	v_lshl_add_u64 v[56:57], v[20:21], 0, v[18:19]
	global_load_dwordx4 v[20:23], v[10:11], off offset:16
	global_load_dwordx4 v[28:31], v[10:11], off
	global_load_dwordx4 v[32:35], v[24:25], off offset:16
	global_load_dwordx4 v[36:39], v[24:25], off
	global_load_dwordx4 v[40:43], v16, s[44:45] offset:16
	global_load_dwordx4 v[44:47], v16, s[44:45]
	v_and_b32_e32 v25, 0xffff0000, v1
	v_lshlrev_b32_e32 v24, 16, v1
	v_and_b32_e32 v75, 0xffff0000, v2
	v_lshlrev_b32_e32 v74, 16, v2
	v_and_b32_e32 v79, 0xffff0000, v3
	v_lshlrev_b32_e32 v78, 16, v3
	global_load_dwordx4 v[0:3], v[10:11], off offset:2064
	global_load_dwordx4 v[48:51], v[10:11], off offset:2048
	global_load_dwordx4 v[52:55], v[56:57], off offset:16
	s_nop 0
	global_load_dwordx4 v[56:59], v[56:57], off
	s_nop 0
	global_load_dwordx4 v[60:63], v16, s[44:45] offset:2064
	global_load_dwordx4 v[64:67], v16, s[44:45] offset:2048
	s_mov_b64 s[0:1], 0x4000
	v_lshl_add_u64 v[150:151], v[8:9], 0, s[0:1]
	s_mov_b64 s[0:1], 0x3000
	v_lshl_add_u64 v[152:153], v[8:9], 0, s[0:1]
	v_lshl_add_u64 v[154:155], v[150:151], 0, v[16:17]
	v_lshl_add_u64 v[156:157], v[152:153], 0, v[16:17]
	v_lshl_add_u64 v[158:159], v[150:151], 0, v[18:19]
	v_lshl_add_u64 v[160:161], v[152:153], 0, v[18:19]
	global_load_dwordx4 v[102:105], v16, s[46:47] offset:16
	global_load_dwordx4 v[106:109], v16, s[46:47]
	global_load_dwordx4 v[110:113], v[154:155], off offset:16
	global_load_dwordx4 v[114:117], v[154:155], off
	global_load_dwordx4 v[118:121], v[156:157], off offset:16
	global_load_dwordx4 v[122:125], v[156:157], off
	global_load_dwordx4 v[126:129], v16, s[46:47] offset:2064
	global_load_dwordx4 v[130:133], v16, s[46:47] offset:2048
	global_load_dwordx4 v[134:137], v[158:159], off offset:16
	global_load_dwordx4 v[138:141], v[158:159], off
	global_load_dwordx4 v[142:145], v[160:161], off offset:16
	global_load_dwordx4 v[146:149], v[160:161], off
	v_pk_mul_f32 v[70:71], v[68:69], v[68:69]
	v_pk_mul_f32 v[72:73], v[24:25], v[24:25]
	v_add_f32_e32 v14, v70, v71
	v_add_f32_e32 v14, v72, v14
	v_pk_mul_f32 v[76:77], v[74:75], v[74:75]
	v_add_f32_e32 v14, v73, v14
	v_add_f32_e32 v14, v76, v14
	v_pk_mul_f32 v[80:81], v[78:79], v[78:79]
	v_add_f32_e32 v14, v77, v14
	s_waitcnt vmcnt(24)
	v_and_b32_e32 v83, 0xffff0000, v4
	v_lshlrev_b32_e32 v82, 16, v4
	v_add_f32_e32 v14, v80, v14
	v_pk_mul_f32 v[84:85], v[82:83], v[82:83]
	v_add_f32_e32 v14, v81, v14
	v_and_b32_e32 v87, 0xffff0000, v5
	v_lshlrev_b32_e32 v86, 16, v5
	v_add_f32_e32 v14, v84, v14
	v_pk_mul_f32 v[4:5], v[86:87], v[86:87]
	v_add_f32_e32 v14, v85, v14
	v_and_b32_e32 v89, 0xffff0000, v6
	v_lshlrev_b32_e32 v88, 16, v6
	v_add_f32_e32 v4, v4, v14
	v_pk_mul_f32 v[90:91], v[88:89], v[88:89]
	v_add_f32_e32 v4, v5, v4
	v_and_b32_e32 v93, 0xffff0000, v7
	v_lshlrev_b32_e32 v92, 16, v7
	v_add_f32_e32 v4, v90, v4
	v_pk_mul_f32 v[6:7], v[92:93], v[92:93]
	v_add_f32_e32 v4, v91, v4
	v_add_f32_e32 v4, v6, v4
	v_add_f32_e32 v4, v7, v4
	s_waitcnt lgkmcnt(0)
	s_nop 1
	v_add_f32_dpp v4, v4, v4 quad_perm:[1,0,3,2] row_mask:0xf bank_mask:0xf
	s_nop 1
	v_add_f32_dpp v4, v4, v4 quad_perm:[2,3,0,1] row_mask:0xf bank_mask:0xf
	s_nop 1
	v_add_f32_dpp v4, v4, v4 row_half_mirror row_mask:0xf bank_mask:0xf
	s_nop 1
	v_add_f32_dpp v4, v4, v4 row_mirror row_mask:0xf bank_mask:0xf
	v_mov_b32_e32 v5, v4
	s_nop 1
	v_permlane16_swap_b32_e32 v4, v5
	v_add_f32_e32 v4, v4, v5
	v_mov_b32_e32 v5, v4
	s_nop 1
	v_permlane32_swap_b32_e32 v4, v5
	v_add_f32_e32 v4, v4, v5
	v_fmamk_f32 v4, v4, 0x3a800000, v231
	v_cmp_gt_f32_e64 s[0:1], s3, v4
	v_mul_f32_e32 v5, 0x4b800000, v4
	s_nop 0
	v_cndmask_b32_e64 v4, v4, v5, s[0:1]
	v_rsq_f32_e32 v4, v4
	s_nop 0
	v_mul_f32_e32 v5, 0x45800000, v4
	v_cndmask_b32_e64 v14, v4, v5, s[0:1]
	v_pk_mul_f32 v[4:5], v[14:15], v[68:69] op_sel_hi:[0,1]
	s_waitcnt vmcnt(18)
	v_pk_mul_f32 v[4:5], v[44:45], v[4:5]
	v_pk_mul_f32 v[6:7], v[14:15], v[86:87] op_sel_hi:[0,1]
	v_pk_fma_f32 v[28:29], v[36:37], v[4:5], v[28:29]
	v_pk_mul_f32 v[4:5], v[14:15], v[24:25] op_sel_hi:[0,1]
	v_pk_mul_f32 v[4:5], v[46:47], v[4:5]
	s_waitcnt vmcnt(12)
	v_pk_mul_f32 v[6:7], v[66:67], v[6:7]
	v_pk_fma_f32 v[30:31], v[38:39], v[4:5], v[30:31]
	v_pk_mul_f32 v[4:5], v[14:15], v[74:75] op_sel_hi:[0,1]
	v_pk_mul_f32 v[4:5], v[40:41], v[4:5]
	v_pk_fma_f32 v[6:7], v[58:59], v[6:7], v[50:51]
	v_pk_fma_f32 v[32:33], v[32:33], v[4:5], v[20:21]
	v_pk_mul_f32 v[4:5], v[14:15], v[78:79] op_sel_hi:[0,1]
	v_pk_mul_f32 v[20:21], v[14:15], v[88:89] op_sel_hi:[0,1]
	v_pk_mul_f32 v[4:5], v[42:43], v[4:5]
	v_pk_mul_f32 v[20:21], v[20:21], v[60:61]
	v_pk_fma_f32 v[34:35], v[34:35], v[4:5], v[22:23]
	v_pk_mul_f32 v[4:5], v[14:15], v[82:83] op_sel_hi:[0,1]
	v_pk_fma_f32 v[0:1], v[52:53], v[20:21], v[0:1]
	v_pk_mul_f32 v[20:21], v[14:15], v[92:93] op_sel_hi:[0,1]
	v_pk_mul_f32 v[4:5], v[64:65], v[4:5]
	v_pk_mul_f32 v[20:21], v[20:21], v[62:63]
	v_pk_fma_f32 v[4:5], v[56:57], v[4:5], v[48:49]
	v_pk_fma_f32 v[2:3], v[54:55], v[20:21], v[2:3]
	global_store_dwordx4 v[10:11], v[28:31], off
	global_store_dwordx4 v[10:11], v[32:35], off offset:16
	global_store_dwordx4 v[10:11], v[4:7], off offset:2048
	global_store_dwordx4 v[10:11], v[0:3], off offset:2064
	v_pk_mul_f32 v[10:11], v[28:29], v[28:29]
	v_pk_mul_f32 v[22:23], v[30:31], v[30:31]
	v_add_f32_e32 v10, v10, v11
	v_add_f32_e32 v10, v22, v10
	v_pk_mul_f32 v[24:25], v[32:33], v[32:33]
	v_add_f32_e32 v10, v23, v10
	v_add_f32_e32 v10, v24, v10
	v_pk_mul_f32 v[36:37], v[34:35], v[34:35]
	v_add_f32_e32 v10, v25, v10
	v_add_f32_e32 v10, v36, v10
	v_pk_mul_f32 v[38:39], v[4:5], v[4:5]
	v_add_f32_e32 v10, v37, v10
	v_add_f32_e32 v10, v38, v10
	v_pk_mul_f32 v[40:41], v[6:7], v[6:7]
	v_add_f32_e32 v10, v39, v10
	v_add_f32_e32 v10, v40, v10
	v_pk_mul_f32 v[42:43], v[0:1], v[0:1]
	v_add_f32_e32 v10, v41, v10
	v_add_f32_e32 v10, v42, v10
	v_pk_mul_f32 v[44:45], v[2:3], v[2:3]
	v_add_f32_e32 v10, v43, v10
	s_mov_b64 s[0:1], 0x3000
	v_add_f32_e32 v10, v44, v10
	v_lshl_add_u64 v[20:21], v[8:9], 0, s[0:1]
	v_add_f32_e32 v10, v45, v10
	s_mov_b64 s[0:1], 0x4000
	v_lshl_add_u64 v[24:25], v[8:9], 0, s[0:1]
	v_mov_b32_e32 v8, v10
	v_lshl_add_u64 v[22:23], v[24:25], 0, v[16:17]
	v_lshl_add_u64 v[52:53], v[20:21], 0, v[16:17]
	v_lshl_add_u64 v[24:25], v[24:25], 0, v[18:19]
	v_lshl_add_u64 v[18:19], v[20:21], 0, v[18:19]
	s_waitcnt lgkmcnt(0)
	s_nop 1
	v_add_f32_dpp v8, v8, v8 quad_perm:[1,0,3,2] row_mask:0xf bank_mask:0xf
	s_nop 1
	v_add_f32_dpp v8, v8, v8 quad_perm:[2,3,0,1] row_mask:0xf bank_mask:0xf
	s_nop 1
	v_add_f32_dpp v8, v8, v8 row_half_mirror row_mask:0xf bank_mask:0xf
	s_nop 1
	v_add_f32_dpp v8, v8, v8 row_mirror row_mask:0xf bank_mask:0xf
	v_mov_b32_e32 v9, v8
	s_nop 1
	v_permlane16_swap_b32_e32 v8, v9
	v_add_f32_e32 v8, v8, v9
	v_mov_b32_e32 v9, v8
	s_nop 1
	v_permlane32_swap_b32_e32 v8, v9
	v_add_f32_e32 v8, v8, v9
	v_fmamk_f32 v8, v8, 0x3a800000, v231
	v_cmp_gt_f32_e64 s[0:1], s3, v8
	v_mul_f32_e32 v9, 0x4b800000, v8
	s_nop 0
	v_cndmask_b32_e64 v8, v8, v9, s[0:1]
	v_rsq_f32_e32 v8, v8
	s_nop 0
	v_mul_f32_e32 v9, 0x45800000, v8
	v_cndmask_b32_e64 v14, v8, v9, s[0:1]
	v_pk_mul_f32 v[28:29], v[28:29], v[14:15] op_sel_hi:[1, 0]
	v_pk_mul_f32 v[4:5], v[4:5], v[14:15] op_sel_hi:[1, 0]
	v_pk_mul_f32 v[6:7], v[6:7], v[14:15] op_sel_hi:[1, 0]
	v_pk_mul_f32 v[0:1], v[0:1], v[14:15] op_sel_hi:[1, 0]
	s_waitcnt vmcnt(4)
	v_pk_mul_f32 v[8:9], v[106:107], v[28:29]
	v_pk_add_f32 v[22:23], v[114:115], 1.0 op_sel_hi:[1, 0]
	v_pk_add_f32 v[28:29], v[112:113], 1.0 op_sel_hi:[1, 0]
	v_pk_fma_f32 v[8:9], v[22:23], v[8:9], v[122:123]
	v_pk_mul_f32 v[22:23], v[30:31], v[14:15] op_sel_hi:[1, 0]
	v_cvt_pk_bf16_f32 v8, v8, v9
	v_pk_mul_f32 v[10:11], v[108:109], v[22:23]
	v_pk_add_f32 v[22:23], v[116:117], 1.0 op_sel_hi:[1, 0]
	s_nop 0
	v_pk_fma_f32 v[10:11], v[22:23], v[10:11], v[124:125]
	v_pk_add_f32 v[22:23], v[110:111], 1.0 op_sel_hi:[1, 0]
	v_cvt_pk_bf16_f32 v9, v10, v11
	v_pk_mul_f32 v[10:11], v[32:33], v[14:15] op_sel_hi:[1, 0]
	s_nop 0
	v_pk_mul_f32 v[10:11], v[10:11], v[102:103]
	s_nop 0
	v_pk_fma_f32 v[10:11], v[10:11], v[22:23], v[118:119]
	v_pk_mul_f32 v[22:23], v[34:35], v[14:15] op_sel_hi:[1, 0]
	v_cvt_pk_bf16_f32 v10, v10, v11
	v_pk_mul_f32 v[22:23], v[22:23], v[104:105]
	s_nop 0
	v_pk_fma_f32 v[22:23], v[22:23], v[28:29], v[120:121]
	s_nop 0
	v_cvt_pk_bf16_f32 v11, v22, v23
	v_bfe_u32 v22, v94, 5, 4
	v_mul_u32_u24_e32 v22, 0x9000, v22
	v_mov_b32_e32 v23, v17
	v_lshl_add_u64 v[22:23], v[22:23], 0, v[12:13]
	v_lshlrev_b64 v[22:23], 6, v[22:23]
	v_lshl_add_u64 v[28:29], s[4:5], 0, v[22:23]
	v_lshlrev_b32_e32 v22, 4, v27
	v_and_b32_e32 v22, 48, v22
	v_mov_b32_e32 v23, v17
	v_lshl_add_u64 v[28:29], v[28:29], 0, v[22:23]
	global_store_dwordx4 v[28:29], v[8:11], off
	v_pk_mul_f32 v[0:1], v[0:1], v[126:127]
	v_pk_mul_f32 v[4:5], v[4:5], v[130:131]
	v_pk_add_f32 v[24:25], v[138:139], 1.0 op_sel_hi:[1, 0]
	v_pk_mul_f32 v[6:7], v[6:7], v[132:133]
	v_pk_fma_f32 v[4:5], v[4:5], v[24:25], v[146:147]
	v_pk_add_f32 v[18:19], v[140:141], 1.0 op_sel_hi:[1, 0]
	v_cvt_pk_bf16_f32 v4, v4, v5
	v_pk_fma_f32 v[6:7], v[6:7], v[18:19], v[148:149]
	s_nop 0
	v_cvt_pk_bf16_f32 v5, v6, v7
	v_pk_add_f32 v[6:7], v[134:135], 1.0 op_sel_hi:[1, 0]
	s_nop 0
	v_pk_fma_f32 v[0:1], v[0:1], v[6:7], v[142:143]
	s_nop 0
	v_cvt_pk_bf16_f32 v6, v0, v1
	v_pk_mul_f32 v[0:1], v[2:3], v[14:15] op_sel_hi:[1, 0]
	v_pk_add_f32 v[2:3], v[136:137], 1.0 op_sel_hi:[1, 0]
	v_pk_mul_f32 v[0:1], v[0:1], v[128:129]
	s_nop 0
	v_pk_fma_f32 v[0:1], v[0:1], v[2:3], v[144:145]
	s_nop 0
	v_cvt_pk_bf16_f32 v7, v0, v1
	v_lshrrev_b32_e32 v0, 5, v26
	v_mul_u32_u24_e32 v16, 0x9000, v0
	v_lshl_add_u64 v[0:1], v[16:17], 0, v[12:13]
	v_lshlrev_b64 v[0:1], 6, v[0:1]
	v_lshl_add_u64 v[0:1], s[4:5], 0, v[0:1]
	v_lshl_add_u64 v[0:1], v[0:1], 0, v[22:23]
	global_store_dwordx4 v[0:1], v[4:7], off
	s_cbranch_scc1 .LBB0_1073
	s_branch .LBB0_1066
